# one static s_setprio 1 for waves 0-3 while they run mixer units (mirror of the waves 4-7 variant)
# speedup vs baseline: 1.0025x; 1.0005x over previous
.LBB0_960:
	s_or_b64 exec, exec, s[0:1]
	v_readfirstlane_b32 s58, v228
	s_lshr_b32 s58, s58, 8
	s_cmp_eq_u32 s58, 0
	s_cbranch_scc0 .Lmy_prio_skip
	s_setprio 1
